# P7/P8 per-tile accumulator zeroing: 128 v_mov_b32 -> 64 v_mov_b64 (on top of VALU-free K-loop load parts)
# baseline (speedup 1.0000x reference)
; template <class Epi>
; __device__ __forceinline__ void gemm_phase(ldsp lds, const Gemm g, const StaticOrder& S, const Epi& E) {
;     ...
;         const bool has_next = S.next(ui + 1, nxt);
;         const char* nA = has_next ? (const char*)g.A + (size_t)nxt.pm * tstep : cA; const char* nB = has_next ? (const char*)g.Bt + (size_t)nxt.pn * tstep : cB;
;     ...
; #pragma unroll
;         for (int a = 0; a < 2; ++a)
; #pragma unroll
;             for (int b = 0; b < 2; ++b)
; #pragma unroll
;                 for (int m = 0; m < 4; ++m)
; #pragma unroll
;                     for (int n = 0; n < 2; ++n) acc[a][b][m][n] = (f32x4){0.f, 0.f, 0.f, 0.f};
;         cur = nxt; cA = nA; cB = nB; ++ui;
.LBB0_815:
	s_ashr_i32 s17, s16, 31
	v_cmp_lt_i64_e32 vcc, s[18:19], v[140:141]
	s_lshl_b64 s[18:19], s[16:17], 20
	s_add_u32 s18, s58, s18
	s_addc_u32 s19, s59, s19
	s_and_b64 s[20:21], vcc, exec
	s_cselect_b32 s17, s19, s27
	s_cselect_b32 s44, s18, s26
	s_ashr_i32 s15, s14, 31
	s_lshl_b64 s[20:21], s[14:15], 20
	s_add_u32 s20, s66, s20
	s_addc_u32 s21, s67, s21
	s_and_b64 s[46:47], vcc, exec
	s_cselect_b32 s15, s21, s25
	s_cselect_b32 s45, s20, s24
	s_waitcnt vmcnt(0)
	v_lshl_add_u32 v160, s22, 8, v174
	s_add_u32 s22, s26, 0x80080
	s_addc_u32 s23, s27, 0
	v_ashrrev_i32_e32 v161, 31, v160
	s_add_u32 s46, s24, 0x100
	v_mov_b64_e32 v[0:1], 0
	v_mov_b64_e32 v[2:3], 0
	v_mov_b64_e32 v[4:5], 0
	v_mov_b64_e32 v[6:7], 0
	v_mov_b64_e32 v[8:9], 0
	v_mov_b64_e32 v[10:11], 0
	v_mov_b64_e32 v[12:13], 0
	v_mov_b64_e32 v[14:15], 0
	v_mov_b64_e32 v[16:17], 0
	v_mov_b64_e32 v[18:19], 0
	v_mov_b64_e32 v[20:21], 0
	v_mov_b64_e32 v[22:23], 0
	v_mov_b64_e32 v[24:25], 0
	v_mov_b64_e32 v[26:27], 0
	v_mov_b64_e32 v[28:29], 0
	v_mov_b64_e32 v[30:31], 0
	v_mov_b64_e32 v[32:33], 0
	v_mov_b64_e32 v[34:35], 0
	v_mov_b64_e32 v[36:37], 0
	v_mov_b64_e32 v[38:39], 0
	v_mov_b64_e32 v[40:41], 0
	v_mov_b64_e32 v[42:43], 0
	v_mov_b64_e32 v[44:45], 0
	v_mov_b64_e32 v[46:47], 0
	v_mov_b64_e32 v[48:49], 0
	v_mov_b64_e32 v[50:51], 0
	v_mov_b64_e32 v[52:53], 0
	v_mov_b64_e32 v[54:55], 0
	v_mov_b64_e32 v[56:57], 0
	v_mov_b64_e32 v[58:59], 0
	v_mov_b64_e32 v[60:61], 0
	v_mov_b64_e32 v[62:63], 0
	v_mov_b64_e32 v[64:65], 0
	v_mov_b64_e32 v[66:67], 0
	v_mov_b64_e32 v[68:69], 0
	v_mov_b64_e32 v[70:71], 0
	v_mov_b64_e32 v[72:73], 0
	v_mov_b64_e32 v[74:75], 0
	v_mov_b64_e32 v[76:77], 0
	v_mov_b64_e32 v[78:79], 0
	v_mov_b64_e32 v[80:81], 0
	v_mov_b64_e32 v[82:83], 0
	v_mov_b64_e32 v[84:85], 0
	v_mov_b64_e32 v[86:87], 0
	v_mov_b64_e32 v[88:89], 0
	v_mov_b64_e32 v[90:91], 0
	v_mov_b64_e32 v[92:93], 0
	v_mov_b64_e32 v[94:95], 0
	v_mov_b64_e32 v[96:97], 0
	v_mov_b64_e32 v[98:99], 0
	v_mov_b64_e32 v[100:101], 0
	v_mov_b64_e32 v[102:103], 0
	v_mov_b64_e32 v[104:105], 0
	v_mov_b64_e32 v[106:107], 0
	v_mov_b64_e32 v[108:109], 0
	v_mov_b64_e32 v[110:111], 0
	v_mov_b64_e32 v[112:113], 0
	v_mov_b64_e32 v[114:115], 0
	v_mov_b64_e32 v[116:117], 0
	v_mov_b64_e32 v[118:119], 0
	v_mov_b64_e32 v[120:121], 0
	v_mov_b64_e32 v[122:123], 0
	v_mov_b64_e32 v[124:125], 0
	v_mov_b64_e32 v[126:127], 0
	v_lshl_add_u64 v[162:163], v[160:161], 3, s[0:1]
	s_addc_u32 s47, s25, 0
	s_mov_b32 s50, -2
	s_branch .LBB0_817

; template <class Epi>
; __device__ __forceinline__ void gemm_phase(ldsp lds, const Gemm g, const StaticOrder& S, const Epi& E) {
;     ...
;         const bool has_next = S.next(ui + 1, nxt);
;         const char* nA = has_next ? (const char*)g.A + (size_t)nxt.pm * tstep : cA; const char* nB = has_next ? (const char*)g.Bt + (size_t)nxt.pn * tstep : cB;
;     ...
; #pragma unroll
;         for (int a = 0; a < 2; ++a)
; #pragma unroll
;             for (int b = 0; b < 2; ++b)
; #pragma unroll
;                 for (int m = 0; m < 4; ++m)
; #pragma unroll
;                     for (int n = 0; n < 2; ++n) acc[a][b][m][n] = (f32x4){0.f, 0.f, 0.f, 0.f};
;         cur = nxt; cA = nA; cB = nB; ++ui;
.LBB0_898:
	s_add_u32 s14, s14, 0x160080
	s_addc_u32 s15, s15, 0
	s_add_u32 s40, s16, 0x100
	v_mov_b64_e32 v[0:1], 0
	v_mov_b64_e32 v[2:3], 0
	v_mov_b64_e32 v[4:5], 0
	v_mov_b64_e32 v[6:7], 0
	v_mov_b64_e32 v[8:9], 0
	v_mov_b64_e32 v[10:11], 0
	v_mov_b64_e32 v[12:13], 0
	v_mov_b64_e32 v[14:15], 0
	v_mov_b64_e32 v[16:17], 0
	v_mov_b64_e32 v[18:19], 0
	v_mov_b64_e32 v[20:21], 0
	v_mov_b64_e32 v[22:23], 0
	v_mov_b64_e32 v[24:25], 0
	v_mov_b64_e32 v[26:27], 0
	v_mov_b64_e32 v[28:29], 0
	v_mov_b64_e32 v[30:31], 0
	v_mov_b64_e32 v[32:33], 0
	v_mov_b64_e32 v[34:35], 0
	v_mov_b64_e32 v[36:37], 0
	v_mov_b64_e32 v[38:39], 0
	v_mov_b64_e32 v[40:41], 0
	v_mov_b64_e32 v[42:43], 0
	v_mov_b64_e32 v[44:45], 0
	v_mov_b64_e32 v[46:47], 0
	v_mov_b64_e32 v[48:49], 0
	v_mov_b64_e32 v[50:51], 0
	v_mov_b64_e32 v[52:53], 0
	v_mov_b64_e32 v[54:55], 0
	v_mov_b64_e32 v[56:57], 0
	v_mov_b64_e32 v[58:59], 0
	v_mov_b64_e32 v[60:61], 0
	v_mov_b64_e32 v[62:63], 0
	v_mov_b64_e32 v[64:65], 0
	v_mov_b64_e32 v[66:67], 0
	v_mov_b64_e32 v[68:69], 0
	v_mov_b64_e32 v[70:71], 0
	v_mov_b64_e32 v[72:73], 0
	v_mov_b64_e32 v[74:75], 0
	v_mov_b64_e32 v[76:77], 0
	v_mov_b64_e32 v[78:79], 0
	v_mov_b64_e32 v[80:81], 0
	v_mov_b64_e32 v[82:83], 0
	v_mov_b64_e32 v[84:85], 0
	v_mov_b64_e32 v[86:87], 0
	v_mov_b64_e32 v[88:89], 0
	v_mov_b64_e32 v[90:91], 0
	v_mov_b64_e32 v[92:93], 0
	v_mov_b64_e32 v[94:95], 0
	v_mov_b64_e32 v[96:97], 0
	v_mov_b64_e32 v[98:99], 0
	v_mov_b64_e32 v[100:101], 0
	v_mov_b64_e32 v[102:103], 0
	v_mov_b64_e32 v[104:105], 0
	v_mov_b64_e32 v[106:107], 0
	v_mov_b64_e32 v[108:109], 0
	v_mov_b64_e32 v[110:111], 0
	v_mov_b64_e32 v[112:113], 0
	v_mov_b64_e32 v[114:115], 0
	v_mov_b64_e32 v[116:117], 0
	v_mov_b64_e32 v[118:119], 0
	v_mov_b64_e32 v[120:121], 0
	v_mov_b64_e32 v[122:123], 0
	v_mov_b64_e32 v[124:125], 0
	v_mov_b64_e32 v[126:127], 0
	s_addc_u32 s41, s17, 0
	s_mov_b32 s42, -2
	s_waitcnt lgkmcnt(0)
	s_waitcnt vmcnt(0)
